# nt hint extended to the prologue f32 weight reads (all read-once inputs of the kernel are now nt)
# baseline (speedup 1.0000x reference)
; #define LAS __attribute__((address_space(3)))
; __device__ __forceinline__ void transpose_item(const float* W, int K, int N, bf16_t* WT, int mapmode, const float* ga, const float* gb, int ksplit, int qcols, LAS float* scr, int item, int lane) {
;     const int nblk = N / 64, kb = item / nblk, nb = item % nblk, k0 = 64 * kb, n0 = 64 * nb;
;     const float cs = (n0 < qcols) ? 0.125f * 1.44269504088896f : 1.0f;
;     const int kl = lane >> 4, n4 = (lane & 15) * 4;
;     f32x4 v[16];
; #pragma unroll
;     for (int i = 0; i < 16; ++i) v[i] = *(const f32x4*)(W + (size_t)(k0 + 4 * i + kl) * N + n0 + n4);
; #pragma unroll
;     for (int i = 0; i < 16; ++i) { const int kk = 4 * i + kl, k = k0 + kk;
;         float g = cs; if (ga) g *= (k < ksplit) ? ga[k] : gb[k - ksplit];
;         LAS float* d = scr + kk * 65 + n4; d[0] = v[i][0] * g; d[1] = v[i][1] * g; d[2] = v[i][2] * g; d[3] = v[i][3] * g; }
; __device__ __forceinline__ void prologue(const Args& A, LAS unsigned char* lds) {
;     ...
;     for (int it = gw; it < DEPTH * PER_L; it += NGW) {
;         const int L = it / PER_L; int r = it % PER_L;
;         unsigned char* wl = A.ws + WS_W + (size_t)L * W_LAYER;
;         if (r < I_IN) { transpose_item(A.in[I_WIN] + (size_t)L * DM * NIN, DM, NIN, (bf16_t*)(wl + WO_IN), 0, A.in[I_GMIX] + L * DM, A.in[I_GMIX] + L * DM, DM, 512, scr, r, lane); continue; } r -= I_IN;
;         if (r < I_OUT) { transpose_item(A.in[I_WOUT] + (size_t)L * DM * DM, DM, DM, (bf16_t*)(wl + WO_OUT), 0, A.in[I_GATT] + L * 512, A.in[I_GCONV] + L * 512, 512, 0, scr, r, lane); continue; } r -= I_OUT;
;         if (r < I_G) { transpose_item(A.in[I_WGATE] + (size_t)L * DM * DFF, DM, DFF, (bf16_t*)(wl + WO_GU), 1, A.in[I_GFFN] + L * DM, A.in[I_GFFN] + L * DM, DM, 0, scr, r, lane); continue; } r -= I_G;
;         if (r < I_G) { transpose_item(A.in[I_WUP] + (size_t)L * DM * DFF, DM, DFF, (bf16_t*)(wl + WO_GU), 2, A.in[I_GFFN] + L * DM, A.in[I_GFFN] + L * DM, DM, 0, scr, r, lane); continue; } r -= I_G;
;         if (r < I_DN) { transpose_item(A.in[I_WDOWN] + (size_t)L * DFF * DM, DFF, DM, (bf16_t*)(wl + WO_DOWN), 0, nullptr, nullptr, 0, 0, scr, r, lane); continue; } r -= I_DN;
;         if (r < I_PG) { transpose_item(A.in[I_WPG] + (size_t)L * DM * DM, DM, DM, (bf16_t*)(wl + WO_PG), 0, A.in[I_GPLE] + L * DM, A.in[I_GPLE] + L * DM, DM, 0, scr, r, lane); continue; } r -= I_PG;
.LBB0_8:
	s_mov_b32 s0, 0x4bda12f7
	v_mul_hi_i32 v2, v130, s0
	v_lshrrev_b32_e32 v3, 31, v2
	v_ashrrev_i32_e32 v2, 10, v2
	v_add_u32_e32 v90, v2, v3
	s_mov_b32 s0, 0x1b00000
	v_mul_i32_i24_e32 v2, 0xd80, v90
	v_mad_i64_i32 v[84:85], s[0:1], v90, s0, v[82:83]
	v_sub_u32_e32 v3, v130, v2
	s_movk_i32 s0, 0x2ff
	v_ashrrev_i32_e32 v91, 31, v90
	v_cmp_lt_i32_e32 vcc, s0, v3
	s_and_saveexec_b64 s[0:1], vcc
	s_xor_b64 s[38:39], exec, s[0:1]
	s_cbranch_execz .LBB0_126
	s_movk_i32 s0, 0x3ff
	v_cmp_lt_u32_e32 vcc, s0, v3
	s_and_saveexec_b64 s[0:1], vcc
	s_xor_b64 s[4:5], exec, s[0:1]
	s_cbranch_execz .LBB0_99
	s_movk_i32 s0, 0x6bf
	v_cmp_lt_u32_e32 vcc, s0, v3
	s_and_saveexec_b64 s[0:1], vcc
	s_xor_b64 s[40:41], exec, s[0:1]
	s_cbranch_execz .LBB0_72
	s_movk_i32 s0, 0x97f
	v_cmp_lt_u32_e32 vcc, s0, v3
	s_and_saveexec_b64 s[0:1], vcc
	s_xor_b64 s[42:43], exec, s[0:1]
	s_cbranch_execz .LBB0_45
	s_movk_i32 s0, 0xc3f
	v_cmp_lt_u32_e32 vcc, s0, v3
	s_and_saveexec_b64 s[0:1], vcc
	s_xor_b64 s[44:45], exec, s[0:1]
	s_cbranch_execz .LBB0_42
	s_movk_i32 s0, 0xd3f
	v_cmp_lt_u32_e32 vcc, s0, v3
	s_and_saveexec_b64 s[0:1], vcc
	s_xor_b64 s[0:1], exec, s[0:1]
	s_cbranch_execz .LBB0_15
	v_lshlrev_b32_e32 v3, 2, v2
	v_lshlrev_b32_e32 v2, 6, v2
	v_sub_u32_e32 v3, v126, v3
	v_sub_u32_e32 v2, v125, v2
	v_lshlrev_b64 v[4:5], 20, v[90:91]
	v_add_u32_e32 v3, 0x300, v3
	v_and_b32_e32 v87, 0x3c0, v2
	v_lshl_add_u64 v[4:5], s[22:23], 0, v[4:5]
	v_and_b32_e32 v86, 0x3c0, v3
	v_lshlrev_b32_e32 v78, 2, v87
	v_or_b32_e32 v6, v86, v74
	v_lshl_add_u64 v[2:3], v[4:5], 0, v[78:79]
	v_lshlrev_b32_e32 v78, 2, v76
	v_lshl_add_u64 v[2:3], v[2:3], 0, v[78:79]
	v_lshlrev_b32_e32 v78, 12, v6
	v_lshl_add_u64 v[62:63], v[2:3], 0, v[78:79]
	v_add_co_u32_e32 v6, vcc, s86, v62
	v_lshlrev_b32_e32 v78, 1, v86
	s_nop 0
	v_addc_co_u32_e32 v7, vcc, 0, v63, vcc
	v_add_co_u32_e32 v10, vcc, s87, v62
	global_load_dwordx4 v[2:5], v[62:63], off nt
	s_nop 0
	global_load_dwordx4 v[6:9], v[6:7], off nt
	v_addc_co_u32_e32 v11, vcc, 0, v63, vcc
	v_add_co_u32_e32 v14, vcc, s89, v62
	s_mov_b64 s[46:47], 0x1a80000
	s_nop 0
	v_addc_co_u32_e32 v15, vcc, 0, v63, vcc
	global_load_dwordx4 v[10:13], v[10:11], off nt
	s_nop 0
	global_load_dwordx4 v[14:17], v[14:15], off nt
	v_add_co_u32_e32 v18, vcc, s90, v62
	s_nop 1
	v_addc_co_u32_e32 v19, vcc, 0, v63, vcc
	v_add_co_u32_e32 v22, vcc, s91, v62
	s_nop 1
	v_addc_co_u32_e32 v23, vcc, 0, v63, vcc
	global_load_dwordx4 v[18:21], v[18:19], off nt
	s_nop 0
	global_load_dwordx4 v[22:25], v[22:23], off nt
	v_add_co_u32_e32 v26, vcc, s92, v62
	s_nop 1
	v_addc_co_u32_e32 v27, vcc, 0, v63, vcc
	v_add_co_u32_e32 v30, vcc, s93, v62
	s_nop 1
	v_addc_co_u32_e32 v31, vcc, 0, v63, vcc
	global_load_dwordx4 v[26:29], v[26:27], off nt
	s_nop 0
	global_load_dwordx4 v[30:33], v[30:31], off nt
	v_add_co_u32_e32 v34, vcc, s94, v62
	s_nop 1
	v_addc_co_u32_e32 v35, vcc, 0, v63, vcc
	v_add_co_u32_e32 v38, vcc, s95, v62
	s_nop 1
	v_addc_co_u32_e32 v39, vcc, 0, v63, vcc
	global_load_dwordx4 v[34:37], v[34:35], off nt
	s_nop 0
	global_load_dwordx4 v[38:41], v[38:39], off nt
	v_add_co_u32_e32 v42, vcc, s96, v62
	s_nop 1
	v_addc_co_u32_e32 v43, vcc, 0, v63, vcc
	v_add_co_u32_e32 v46, vcc, s60, v62
	s_nop 1
	v_addc_co_u32_e32 v47, vcc, 0, v63, vcc
	global_load_dwordx4 v[42:45], v[42:43], off nt
	s_nop 0
	global_load_dwordx4 v[46:49], v[46:47], off nt
	v_add_co_u32_e32 v50, vcc, s61, v62
	s_nop 1
	v_addc_co_u32_e32 v51, vcc, 0, v63, vcc
	global_load_dwordx4 v[50:53], v[50:51], off nt
	v_add_co_u32_e32 v54, vcc, s62, v62
	s_nop 1
	v_addc_co_u32_e32 v55, vcc, 0, v63, vcc
	global_load_dwordx4 v[54:57], v[54:55], off nt
	v_add_co_u32_e32 v58, vcc, s63, v62
	s_nop 1
	v_addc_co_u32_e32 v59, vcc, 0, v63, vcc
	global_load_dwordx4 v[58:61], v[58:59], off nt
	v_add_co_u32_e32 v62, vcc, s64, v62
	s_nop 1
	v_addc_co_u32_e32 v63, vcc, 0, v63, vcc
	global_load_dwordx4 v[62:65], v[62:63], off nt
	s_waitcnt vmcnt(15)
	ds_write2_b32 v69, v2, v3 offset1:1
	ds_write2_b32 v69, v4, v5 offset0:2 offset1:3
	v_add_u32_e32 v2, 0x410, v69
	s_waitcnt vmcnt(14)
	ds_write2_b32 v2, v6, v7 offset1:1
	v_add_u32_e32 v2, 0x418, v69
	ds_write2_b32 v2, v8, v9 offset1:1
	v_add_u32_e32 v2, 0x820, v69
	v_lshl_add_u64 v[8:9], v[84:85], 0, v[78:79]
	v_lshlrev_b32_e32 v78, 1, v80
	s_waitcnt vmcnt(13)
	ds_write2_b32 v2, v10, v11 offset1:1
	v_add_u32_e32 v2, 0x828, v69
	ds_write2_b32 v2, v12, v13 offset1:1
	v_add_u32_e32 v2, 0xc30, v69
	s_waitcnt vmcnt(12)
	ds_write2_b32 v2, v14, v15 offset1:1
	v_add_u32_e32 v2, 0xc38, v69
	ds_write2_b32 v2, v16, v17 offset1:1
	v_add_u32_e32 v2, 0x1040, v69
	v_add_u32_e32 v12, 0x400, v131
	v_lshl_add_u64 v[8:9], v[8:9], 0, v[78:79]
	v_or_b32_e32 v10, v87, v71
	v_lshl_add_u64 v[8:9], v[8:9], 0, s[46:47]
	s_waitcnt vmcnt(11)
	ds_write2_b32 v2, v18, v19 offset1:1
	v_add_u32_e32 v2, 0x1048, v69
	ds_write2_b32 v2, v20, v21 offset1:1
	v_add_u32_e32 v2, 0x1450, v69
	s_waitcnt vmcnt(10)
	ds_write2_b32 v2, v22, v23 offset1:1
	v_add_u32_e32 v2, 0x1458, v69
	ds_write2_b32 v2, v24, v25 offset1:1
	v_add_u32_e32 v2, 0x1860, v69
	v_lshlrev_b32_e32 v78, 9, v10
	v_lshl_add_u64 v[10:11], v[8:9], 0, v[78:79]
	s_waitcnt vmcnt(9)
	ds_write2_b32 v2, v26, v27 offset1:1
	v_add_u32_e32 v2, 0x1868, v69
	ds_write2_b32 v2, v28, v29 offset1:1
	v_add_u32_e32 v2, 0x1c70, v69
	s_waitcnt vmcnt(8)
	ds_write2_b32 v2, v30, v31 offset1:1
	v_add_u32_e32 v2, 0x1c78, v69
	ds_write2_b32 v2, v32, v33 offset1:1
	v_add_u32_e32 v2, 0x2080, v69
	s_waitcnt vmcnt(7)
	ds_write2_b32 v2, v34, v35 offset1:1
	v_add_u32_e32 v2, 0x2088, v69
	ds_write2_b32 v2, v36, v37 offset1:1
	v_add_u32_e32 v2, 0x2490, v69
	s_waitcnt vmcnt(6)
; __device__ __forceinline__ unsigned cvt_pk_bf16(float lo, float hi) { unsigned r; asm volatile("v_cvt_pk_bf16_f32 %0, %1, %2" : "=v"(r) : "v"(lo), "v"(hi)); return r; }
; #define LAS __attribute__((address_space(3)))
; __device__ __forceinline__ void transpose_item(const float* W, int K, int N, bf16_t* WT, int mapmode, const float* ga, const float* gb, int ksplit, int qcols, LAS float* scr, int item, int lane) {
;     ...
;         LAS float* d = scr + kk * 65 + n4; d[0] = v[i][0] * g; d[1] = v[i][1] * g; d[2] = v[i][2] * g; d[3] = v[i][3] * g; }
;     asm volatile("s_waitcnt lgkmcnt(0)" ::: "memory");
;     const int c = lane & 7;
;     const int rbase = (mapmode == 0) ? n0 : (256 * (n0 >> 7) + (n0 & 127) + (mapmode == 2 ? 128 : 0));
; #pragma unroll
;     for (int j = 0; j < 8; ++j) { const int n = (lane >> 3) + 8 * j; const LAS float* sp = scr + (8 * c) * 65 + n;
;         u32x4 o; o.x = pg8::cvt_pk_bf16(sp[0 * 65], sp[1 * 65]); o.y = pg8::cvt_pk_bf16(sp[2 * 65], sp[3 * 65]); o.z = pg8::cvt_pk_bf16(sp[4 * 65], sp[5 * 65]); o.w = pg8::cvt_pk_bf16(sp[6 * 65], sp[7 * 65]);
;         *(u32x4*)(WT + (size_t)(rbase + n) * K + k0 + 8 * c) = o; }
;     asm volatile("s_waitcnt lgkmcnt(0)" ::: "memory");
	ds_write2_b32 v2, v38, v39 offset1:1
	v_add_u32_e32 v2, 0x2498, v69
	ds_write2_b32 v2, v40, v41 offset1:1
	v_add_u32_e32 v2, 0x28a0, v69
	s_waitcnt vmcnt(5)
	ds_write2_b32 v2, v42, v43 offset1:1
	v_add_u32_e32 v2, 0x28a8, v69
	ds_write2_b32 v2, v44, v45 offset1:1
	v_add_u32_e32 v2, 0x2cb0, v69
	s_waitcnt vmcnt(4)
	ds_write2_b32 v2, v46, v47 offset1:1
	v_add_u32_e32 v2, 0x2cb8, v69
	ds_write2_b32 v2, v48, v49 offset1:1
	v_add_u32_e32 v2, 0x30c0, v69
	s_waitcnt vmcnt(3)
	ds_write2_b32 v2, v50, v51 offset1:1
	v_add_u32_e32 v2, 0x30c8, v69
	ds_write2_b32 v2, v52, v53 offset1:1
	v_add_u32_e32 v2, 0x34d0, v69
	s_waitcnt vmcnt(2)
	ds_write2_b32 v2, v54, v55 offset1:1
	v_add_u32_e32 v2, 0x34d8, v69
	ds_write2_b32 v2, v56, v57 offset1:1
	v_add_u32_e32 v2, 0x38e0, v69
	s_waitcnt vmcnt(1)
	ds_write2_b32 v2, v58, v59 offset1:1
	v_add_u32_e32 v2, 0x38e8, v69
	ds_write2_b32 v2, v60, v61 offset1:1
	v_add_u32_e32 v2, 0x3cf0, v69
	s_waitcnt vmcnt(0)
	ds_write2_b32 v2, v62, v63 offset1:1
	v_add_u32_e32 v2, 0x3cf8, v69
	ds_write2_b32 v2, v64, v65 offset1:1
	s_waitcnt lgkmcnt(0)
	ds_read2_b32 v[2:3], v131 offset1:65
	s_waitcnt lgkmcnt(0)
	v_cvt_pk_bf16_f32 v2, v2, v3
	ds_read2_b32 v[4:5], v131 offset0:130 offset1:195
	s_waitcnt lgkmcnt(0)
	v_cvt_pk_bf16_f32 v3, v4, v5
	ds_read2_b32 v[4:5], v12 offset0:4 offset1:69
	s_waitcnt lgkmcnt(0)
	v_cvt_pk_bf16_f32 v4, v4, v5
	ds_read2_b32 v[6:7], v12 offset0:134 offset1:199
	s_waitcnt lgkmcnt(0)
	v_cvt_pk_bf16_f32 v5, v6, v7
	ds_read2_b32 v[6:7], v131 offset0:8 offset1:73
	global_store_dwordx4 v[10:11], v[2:5], off
	v_or_b32_e32 v10, v87, v73
	v_lshlrev_b32_e32 v78, 9, v10
	s_waitcnt lgkmcnt(0)
	v_cvt_pk_bf16_f32 v2, v6, v7
	ds_read2_b32 v[4:5], v131 offset0:138 offset1:203
	s_waitcnt lgkmcnt(0)
	v_cvt_pk_bf16_f32 v3, v4, v5
	ds_read2_b32 v[4:5], v12 offset0:12 offset1:77
	s_waitcnt lgkmcnt(0)
	v_cvt_pk_bf16_f32 v4, v4, v5
	ds_read2_b32 v[6:7], v12 offset0:142 offset1:207
	s_waitcnt lgkmcnt(0)
	v_cvt_pk_bf16_f32 v5, v6, v7
	v_lshl_add_u64 v[10:11], v[8:9], 0, v[78:79]
	ds_read2_b32 v[6:7], v131 offset0:16 offset1:81
	global_store_dwordx4 v[10:11], v[2:5], off
	v_or_b32_e32 v10, v87, v77
	v_lshlrev_b32_e32 v78, 9, v10
	s_waitcnt lgkmcnt(0)
	v_cvt_pk_bf16_f32 v2, v6, v7
	ds_read2_b32 v[4:5], v131 offset0:146 offset1:211
	s_waitcnt lgkmcnt(0)
	v_cvt_pk_bf16_f32 v3, v4, v5
	ds_read2_b32 v[4:5], v12 offset0:20 offset1:85
	s_waitcnt lgkmcnt(0)
	v_cvt_pk_bf16_f32 v4, v4, v5
	ds_read2_b32 v[6:7], v12 offset0:150 offset1:215
	s_waitcnt lgkmcnt(0)
	v_cvt_pk_bf16_f32 v5, v6, v7
	v_lshl_add_u64 v[10:11], v[8:9], 0, v[78:79]
	ds_read2_b32 v[6:7], v131 offset0:24 offset1:89
	global_store_dwordx4 v[10:11], v[2:5], off
	v_or_b32_e32 v10, v87, v81
	v_lshlrev_b32_e32 v78, 9, v10
	s_waitcnt lgkmcnt(0)
	v_cvt_pk_bf16_f32 v2, v6, v7
	ds_read2_b32 v[4:5], v131 offset0:154 offset1:219
	s_waitcnt lgkmcnt(0)
	v_cvt_pk_bf16_f32 v3, v4, v5
	ds_read2_b32 v[4:5], v12 offset0:28 offset1:93
	s_waitcnt lgkmcnt(0)
	v_cvt_pk_bf16_f32 v4, v4, v5
	ds_read2_b32 v[6:7], v12 offset0:158 offset1:223
	s_waitcnt lgkmcnt(0)
	v_cvt_pk_bf16_f32 v5, v6, v7
	v_lshl_add_u64 v[10:11], v[8:9], 0, v[78:79]
	ds_read2_b32 v[6:7], v131 offset0:32 offset1:97
	global_store_dwordx4 v[10:11], v[2:5], off
	v_or_b32_e32 v10, v87, v95
	v_lshlrev_b32_e32 v78, 9, v10
	s_waitcnt lgkmcnt(0)
	v_cvt_pk_bf16_f32 v2, v6, v7
	ds_read2_b32 v[4:5], v131 offset0:162 offset1:227
	s_waitcnt lgkmcnt(0)
	v_cvt_pk_bf16_f32 v3, v4, v5
	ds_read2_b32 v[4:5], v12 offset0:36 offset1:101
	s_waitcnt lgkmcnt(0)
	v_cvt_pk_bf16_f32 v4, v4, v5
	ds_read2_b32 v[6:7], v12 offset0:166 offset1:231
	s_waitcnt lgkmcnt(0)
	v_cvt_pk_bf16_f32 v5, v6, v7
	v_lshl_add_u64 v[10:11], v[8:9], 0, v[78:79]
	ds_read2_b32 v[6:7], v131 offset0:40 offset1:105
	global_store_dwordx4 v[10:11], v[2:5], off
	v_or_b32_e32 v10, v87, v96
	v_lshlrev_b32_e32 v78, 9, v10
	s_waitcnt lgkmcnt(0)
	v_cvt_pk_bf16_f32 v2, v6, v7
	ds_read2_b32 v[4:5], v131 offset0:170 offset1:235
	s_waitcnt lgkmcnt(0)
	v_cvt_pk_bf16_f32 v3, v4, v5
	ds_read2_b32 v[4:5], v12 offset0:44 offset1:109
	s_waitcnt lgkmcnt(0)
	v_cvt_pk_bf16_f32 v4, v4, v5
	ds_read2_b32 v[6:7], v12 offset0:174 offset1:239
	s_waitcnt lgkmcnt(0)
	v_cvt_pk_bf16_f32 v5, v6, v7
	v_lshl_add_u64 v[10:11], v[8:9], 0, v[78:79]
	ds_read2_b32 v[6:7], v131 offset0:48 offset1:113
	global_store_dwordx4 v[10:11], v[2:5], off
	v_or_b32_e32 v10, v87, v97
	v_lshlrev_b32_e32 v78, 9, v10
	s_waitcnt lgkmcnt(0)
	v_cvt_pk_bf16_f32 v2, v6, v7
	ds_read2_b32 v[4:5], v131 offset0:178 offset1:243
	s_waitcnt lgkmcnt(0)
	v_cvt_pk_bf16_f32 v3, v4, v5
	ds_read2_b32 v[4:5], v12 offset0:52 offset1:117
	s_waitcnt lgkmcnt(0)
	v_cvt_pk_bf16_f32 v4, v4, v5
	ds_read2_b32 v[6:7], v12 offset0:182 offset1:247
	s_waitcnt lgkmcnt(0)
	v_cvt_pk_bf16_f32 v5, v6, v7
	v_lshl_add_u64 v[10:11], v[8:9], 0, v[78:79]
	ds_read2_b32 v[6:7], v131 offset0:56 offset1:121
	global_store_dwordx4 v[10:11], v[2:5], off
	s_waitcnt lgkmcnt(0)
	s_nop 0
	v_cvt_pk_bf16_f32 v2, v6, v7
	ds_read2_b32 v[4:5], v131 offset0:186 offset1:251
	s_waitcnt lgkmcnt(0)
	v_cvt_pk_bf16_f32 v3, v4, v5
	ds_read2_b32 v[4:5], v12 offset0:60 offset1:125
	s_waitcnt lgkmcnt(0)
	v_cvt_pk_bf16_f32 v4, v4, v5
	ds_read2_b32 v[6:7], v12 offset0:190 offset1:255
	s_waitcnt lgkmcnt(0)
	v_cvt_pk_bf16_f32 v5, v6, v7
	v_or_b32_e32 v6, v87, v98
	v_lshlrev_b32_e32 v78, 9, v6
	v_lshl_add_u64 v[6:7], v[8:9], 0, v[78:79]
	global_store_dwordx4 v[6:7], v[2:5], off
	s_waitcnt lgkmcnt(0)
; #define LAS __attribute__((address_space(3)))
; __device__ __forceinline__ void transpose_item(const float* W, int K, int N, bf16_t* WT, int mapmode, const float* ga, const float* gb, int ksplit, int qcols, LAS float* scr, int item, int lane) {
;     ...
;     for (int i = 0; i < 16; ++i) v[i] = *(const f32x4*)(W + (size_t)(k0 + 4 * i + kl) * N + n0 + n4);
; #pragma unroll
;     for (int i = 0; i < 16; ++i) { const int kk = 4 * i + kl, k = k0 + kk;
;         float g = cs; if (ga) g *= (k < ksplit) ? ga[k] : gb[k - ksplit];
;         LAS float* d = scr + kk * 65 + n4; d[0] = v[i][0] * g; d[1] = v[i][1] * g; d[2] = v[i][2] * g; d[3] = v[i][3] * g; }
; __device__ __forceinline__ void prologue(const Args& A, LAS unsigned char* lds) {
;     ...
;         if (r < I_PG) { transpose_item(A.in[I_WPG] + (size_t)L * DM * DM, DM, DM, (bf16_t*)(wl + WO_PG), 0, A.in[I_GPLE] + L * DM, A.in[I_GPLE] + L * DM, DM, 0, scr, r, lane); continue; } r -= I_PG;
.LBB0_15:
	s_andn2_saveexec_b64 s[46:47], s[0:1]
	s_cbranch_execz .LBB0_41
	v_lshlrev_b32_e32 v3, 2, v2
	v_lshlrev_b32_e32 v2, 6, v2
	v_sub_u32_e32 v3, v126, v3
	v_sub_u32_e32 v2, v125, v2
	v_lshlrev_b64 v[4:5], 22, v[90:91]
	v_add_u32_e32 v3, 0x300, v3
	v_and_b32_e32 v87, 0x3c0, v2
	v_lshl_add_u64 v[4:5], s[20:21], 0, v[4:5]
	v_and_b32_e32 v86, 0x3c0, v3
	v_lshlrev_b32_e32 v78, 2, v87
	v_or_b32_e32 v91, v86, v74
	v_lshl_add_u64 v[2:3], v[4:5], 0, v[78:79]
	v_lshlrev_b32_e32 v78, 2, v76
	v_lshl_add_u64 v[2:3], v[2:3], 0, v[78:79]
	v_lshlrev_b32_e32 v78, 12, v91
	v_lshl_add_u64 v[2:3], v[2:3], 0, v[78:79]
	v_add_co_u32_e32 v4, vcc, s86, v2
	v_lshlrev_b32_e32 v88, 10, v90
	s_nop 0
	v_addc_co_u32_e32 v5, vcc, 0, v3, vcc
	global_load_dwordx4 v[62:65], v[2:3], off nt
	global_load_dwordx4 v[58:61], v[4:5], off nt
	v_add_co_u32_e32 v4, vcc, s87, v2
	v_ashrrev_i32_e32 v89, 31, v88
	s_nop 0
	v_addc_co_u32_e32 v5, vcc, 0, v3, vcc
	v_add_co_u32_e32 v6, vcc, s89, v2
	v_cndmask_b32_e64 v78, 0, 1, s[24:25]
	s_nop 0
	v_addc_co_u32_e32 v7, vcc, 0, v3, vcc
	global_load_dwordx4 v[54:57], v[4:5], off nt
	global_load_dwordx4 v[50:53], v[6:7], off nt
	v_add_co_u32_e32 v4, vcc, s90, v2
	v_lshl_add_u64 v[88:89], v[88:89], 2, s[18:19]
	s_nop 0
	v_addc_co_u32_e32 v5, vcc, 0, v3, vcc
	v_add_co_u32_e32 v6, vcc, s91, v2
	v_cmp_ne_u32_e64 s[0:1], 1, v78
	s_nop 0
	v_addc_co_u32_e32 v7, vcc, 0, v3, vcc
	global_load_dwordx4 v[46:49], v[4:5], off nt
	global_load_dwordx4 v[42:45], v[6:7], off nt
	v_add_co_u32_e32 v4, vcc, s92, v2
	v_add_lshl_u32 v90, v86, v74, 2
	s_nop 0
	v_addc_co_u32_e32 v5, vcc, 0, v3, vcc
	v_add_co_u32_e32 v6, vcc, s93, v2
	s_nop 1
	v_addc_co_u32_e32 v7, vcc, 0, v3, vcc
	global_load_dwordx4 v[38:41], v[4:5], off nt
	global_load_dwordx4 v[34:37], v[6:7], off nt
	v_add_co_u32_e32 v4, vcc, s94, v2
	s_nop 1
	v_addc_co_u32_e32 v5, vcc, 0, v3, vcc
	v_add_co_u32_e32 v6, vcc, s95, v2
	s_nop 1
	v_addc_co_u32_e32 v7, vcc, 0, v3, vcc
	global_load_dwordx4 v[30:33], v[4:5], off nt
	global_load_dwordx4 v[26:29], v[6:7], off nt
	v_add_co_u32_e32 v4, vcc, s96, v2
	s_nop 1
	v_addc_co_u32_e32 v5, vcc, 0, v3, vcc
	v_add_co_u32_e32 v6, vcc, s60, v2
	s_nop 1
	v_addc_co_u32_e32 v7, vcc, 0, v3, vcc
	global_load_dwordx4 v[22:25], v[4:5], off nt
	global_load_dwordx4 v[18:21], v[6:7], off nt
	v_add_co_u32_e32 v4, vcc, s61, v2
	s_nop 1
	v_addc_co_u32_e32 v5, vcc, 0, v3, vcc
	v_add_co_u32_e32 v6, vcc, 0x34000, v2
	s_nop 1
	v_addc_co_u32_e32 v7, vcc, 0, v3, vcc
	global_load_dwordx4 v[14:17], v[4:5], off nt
	global_load_dwordx4 v[10:13], v[6:7], off nt
	v_add_co_u32_e32 v4, vcc, 0x38000, v2
	s_nop 1
	v_addc_co_u32_e32 v5, vcc, 0, v3, vcc
	v_add_co_u32_e32 v2, vcc, 0x3c000, v2
	s_nop 1
	v_addc_co_u32_e32 v3, vcc, 0, v3, vcc
	global_load_dwordx4 v[6:9], v[4:5], off nt
	s_nop 0
	global_load_dwordx4 v[2:5], v[2:3], off nt
	s_andn2_b64 vcc, exec, s[24:25]
	s_cbranch_vccnz .LBB0_183
	v_lshlrev_b32_e32 v78, 2, v91
	v_lshl_add_u64 v[92:93], v[88:89], 0, v[78:79]
	v_mov_b32_e32 v91, v79
	global_load_dword v92, v[92:93], off
	v_lshl_add_u64 v[132:133], v[88:89], 0, v[90:91]
	global_load_dword v78, v[132:133], off offset:16
	s_waitcnt vmcnt(1)
	v_pk_mul_f32 v[132:133], v[62:63], v[92:93] op_sel_hi:[1,0]
	v_pk_mul_f32 v[92:93], v[64:65], v[92:93] op_sel_hi:[1,0]
	ds_write2_b32 v69, v132, v133 offset1:1
	ds_write2_b32 v69, v92, v93 offset0:2 offset1:3
	s_cbranch_execnz .LBB0_19

; #define LAS __attribute__((address_space(3)))
; __device__ __forceinline__ void transpose_item(const float* W, int K, int N, bf16_t* WT, int mapmode, const float* ga, const float* gb, int ksplit, int qcols, LAS float* scr, int item, int lane) {
;     ...
;     for (int i = 0; i < 16; ++i) v[i] = *(const f32x4*)(W + (size_t)(k0 + 4 * i + kl) * N + n0 + n4);
; #pragma unroll
;     for (int i = 0; i < 16; ++i) { const int kk = 4 * i + kl, k = k0 + kk;
;         float g = cs; if (ga) g *= (k < ksplit) ? ga[k] : gb[k - ksplit];
;         LAS float* d = scr + kk * 65 + n4; d[0] = v[i][0] * g; d[1] = v[i][1] * g; d[2] = v[i][2] * g; d[3] = v[i][3] * g; }
; __device__ __forceinline__ void prologue(const Args& A, LAS unsigned char* lds) {
;     ...
;         if (r < I_DN) { transpose_item(A.in[I_WDOWN] + (size_t)L * DFF * DM, DFF, DM, (bf16_t*)(wl + WO_DOWN), 0, nullptr, nullptr, 0, 0, scr, r, lane); continue; } r -= I_DN;
.LBB0_42:
	s_andn2_saveexec_b64 s[0:1], s[44:45]
	s_cbranch_execz .LBB0_44
	v_lshlrev_b32_e32 v3, 2, v2
	v_lshlrev_b32_e32 v2, 6, v2
	v_sub_u32_e32 v3, v126, v3
	v_sub_u32_e32 v2, v125, v2
	v_mov_b64_e32 v[4:5], s[16:17]
	v_add_u32_e32 v3, 0x3da00, v3
	v_and_b32_e32 v87, 0x3c0, v2
	v_mad_i64_i32 v[4:5], s[44:45], v90, s65, v[4:5]
	v_and_b32_e32 v86, 0x3ffc0, v3
	v_lshlrev_b32_e32 v78, 2, v87
	v_or_b32_e32 v6, v86, v74
	v_lshl_add_u64 v[2:3], v[4:5], 0, v[78:79]
	v_lshlrev_b32_e32 v78, 2, v76
	v_lshl_add_u64 v[2:3], v[2:3], 0, v[78:79]
	v_lshlrev_b32_e32 v78, 12, v6
	v_lshl_add_u64 v[62:63], v[2:3], 0, v[78:79]
	v_add_co_u32_e32 v6, vcc, s86, v62
	v_lshlrev_b32_e32 v78, 1, v86
	s_nop 0
	v_addc_co_u32_e32 v7, vcc, 0, v63, vcc
	v_add_co_u32_e32 v10, vcc, s87, v62
	global_load_dwordx4 v[2:5], v[62:63], off nt
	s_nop 0
	global_load_dwordx4 v[6:9], v[6:7], off nt
	v_addc_co_u32_e32 v11, vcc, 0, v63, vcc
	v_add_co_u32_e32 v14, vcc, s89, v62
	s_mov_b64 s[44:45], 0x1300000
	s_nop 0
	v_addc_co_u32_e32 v15, vcc, 0, v63, vcc
	global_load_dwordx4 v[10:13], v[10:11], off nt
	s_nop 0
	global_load_dwordx4 v[14:17], v[14:15], off nt
	v_add_co_u32_e32 v18, vcc, s90, v62
	s_nop 1
	v_addc_co_u32_e32 v19, vcc, 0, v63, vcc
	v_add_co_u32_e32 v22, vcc, s91, v62
	s_nop 1
	v_addc_co_u32_e32 v23, vcc, 0, v63, vcc
	global_load_dwordx4 v[18:21], v[18:19], off nt
	s_nop 0
	global_load_dwordx4 v[22:25], v[22:23], off nt
	v_add_co_u32_e32 v26, vcc, s92, v62
	s_nop 1
	v_addc_co_u32_e32 v27, vcc, 0, v63, vcc
	v_add_co_u32_e32 v30, vcc, s93, v62
	s_nop 1
	v_addc_co_u32_e32 v31, vcc, 0, v63, vcc
	global_load_dwordx4 v[26:29], v[26:27], off nt
	s_nop 0
	global_load_dwordx4 v[30:33], v[30:31], off nt
	v_add_co_u32_e32 v34, vcc, s94, v62
	s_nop 1
	v_addc_co_u32_e32 v35, vcc, 0, v63, vcc
	v_add_co_u32_e32 v38, vcc, s95, v62
	s_nop 1
	v_addc_co_u32_e32 v39, vcc, 0, v63, vcc
	global_load_dwordx4 v[34:37], v[34:35], off nt
	s_nop 0
	global_load_dwordx4 v[38:41], v[38:39], off nt
	v_add_co_u32_e32 v42, vcc, s96, v62
	s_nop 1
	v_addc_co_u32_e32 v43, vcc, 0, v63, vcc
	v_add_co_u32_e32 v46, vcc, s60, v62
	s_nop 1
	v_addc_co_u32_e32 v47, vcc, 0, v63, vcc
	global_load_dwordx4 v[42:45], v[42:43], off nt
	s_nop 0
	global_load_dwordx4 v[46:49], v[46:47], off nt
	v_add_co_u32_e32 v50, vcc, s61, v62
	s_nop 1
	v_addc_co_u32_e32 v51, vcc, 0, v63, vcc
	global_load_dwordx4 v[50:53], v[50:51], off nt
	v_add_co_u32_e32 v54, vcc, s62, v62
	s_nop 1
	v_addc_co_u32_e32 v55, vcc, 0, v63, vcc
	global_load_dwordx4 v[54:57], v[54:55], off nt
	v_add_co_u32_e32 v58, vcc, s63, v62
	s_nop 1
	v_addc_co_u32_e32 v59, vcc, 0, v63, vcc
	global_load_dwordx4 v[58:61], v[58:59], off nt
	v_add_co_u32_e32 v62, vcc, s64, v62
	s_nop 1
	v_addc_co_u32_e32 v63, vcc, 0, v63, vcc
	global_load_dwordx4 v[62:65], v[62:63], off nt
	s_waitcnt vmcnt(15)
	ds_write2_b32 v69, v2, v3 offset1:1
	ds_write2_b32 v69, v4, v5 offset0:2 offset1:3
	v_add_u32_e32 v2, 0x410, v69
	s_waitcnt vmcnt(14)
	ds_write2_b32 v2, v6, v7 offset1:1
	v_add_u32_e32 v2, 0x418, v69
	ds_write2_b32 v2, v8, v9 offset1:1
	v_add_u32_e32 v2, 0x820, v69
	v_lshl_add_u64 v[8:9], v[84:85], 0, v[78:79]
	v_lshlrev_b32_e32 v78, 1, v80
	s_waitcnt vmcnt(13)
	ds_write2_b32 v2, v10, v11 offset1:1
	v_add_u32_e32 v2, 0x828, v69
	ds_write2_b32 v2, v12, v13 offset1:1
	v_add_u32_e32 v2, 0xc30, v69
	s_waitcnt vmcnt(12)
	ds_write2_b32 v2, v14, v15 offset1:1
	v_add_u32_e32 v2, 0xc38, v69
	ds_write2_b32 v2, v16, v17 offset1:1
	v_add_u32_e32 v2, 0x1040, v69
	v_or_b32_e32 v10, v87, v71
	v_lshl_add_u64 v[8:9], v[8:9], 0, v[78:79]
	v_mul_u32_u24_e32 v10, 0xb00, v10
	s_waitcnt vmcnt(11)
	ds_write2_b32 v2, v18, v19 offset1:1
	v_add_u32_e32 v2, 0x1048, v69
	ds_write2_b32 v2, v20, v21 offset1:1
	v_add_u32_e32 v2, 0x1450, v69
	s_waitcnt vmcnt(10)
	ds_write2_b32 v2, v22, v23 offset1:1
	v_add_u32_e32 v2, 0x1458, v69
	ds_write2_b32 v2, v24, v25 offset1:1
	v_add_u32_e32 v2, 0x1860, v69
	v_add_u32_e32 v12, 0x400, v131
	v_lshl_add_u64 v[8:9], v[8:9], 0, s[44:45]
	v_lshlrev_b32_e32 v78, 1, v10
	s_waitcnt vmcnt(9)
	ds_write2_b32 v2, v26, v27 offset1:1
	v_add_u32_e32 v2, 0x1868, v69
	ds_write2_b32 v2, v28, v29 offset1:1
	v_add_u32_e32 v2, 0x1c70, v69
	s_waitcnt vmcnt(8)
	ds_write2_b32 v2, v30, v31 offset1:1
	v_add_u32_e32 v2, 0x1c78, v69
	ds_write2_b32 v2, v32, v33 offset1:1
	v_add_u32_e32 v2, 0x2080, v69
	v_lshl_add_u64 v[10:11], v[8:9], 0, v[78:79]
	s_waitcnt vmcnt(7)
	ds_write2_b32 v2, v34, v35 offset1:1
	v_add_u32_e32 v2, 0x2088, v69
	ds_write2_b32 v2, v36, v37 offset1:1
	v_add_u32_e32 v2, 0x2490, v69
	s_waitcnt vmcnt(6)
	ds_write2_b32 v2, v38, v39 offset1:1
	v_add_u32_e32 v2, 0x2498, v69
	ds_write2_b32 v2, v40, v41 offset1:1
	v_add_u32_e32 v2, 0x28a0, v69
	s_waitcnt vmcnt(5)
	ds_write2_b32 v2, v42, v43 offset1:1
	v_add_u32_e32 v2, 0x28a8, v69
	ds_write2_b32 v2, v44, v45 offset1:1
	v_add_u32_e32 v2, 0x2cb0, v69
	s_waitcnt vmcnt(4)
	ds_write2_b32 v2, v46, v47 offset1:1
	v_add_u32_e32 v2, 0x2cb8, v69
	ds_write2_b32 v2, v48, v49 offset1:1
	v_add_u32_e32 v2, 0x30c0, v69
	s_waitcnt vmcnt(3)
	ds_write2_b32 v2, v50, v51 offset1:1
	v_add_u32_e32 v2, 0x30c8, v69
	ds_write2_b32 v2, v52, v53 offset1:1
	v_add_u32_e32 v2, 0x34d0, v69
	s_waitcnt vmcnt(2)
; __device__ __forceinline__ unsigned cvt_pk_bf16(float lo, float hi) { unsigned r; asm volatile("v_cvt_pk_bf16_f32 %0, %1, %2" : "=v"(r) : "v"(lo), "v"(hi)); return r; }
; #define LAS __attribute__((address_space(3)))
; __device__ __forceinline__ void transpose_item(const float* W, int K, int N, bf16_t* WT, int mapmode, const float* ga, const float* gb, int ksplit, int qcols, LAS float* scr, int item, int lane) {
;     ...
;         LAS float* d = scr + kk * 65 + n4; d[0] = v[i][0] * g; d[1] = v[i][1] * g; d[2] = v[i][2] * g; d[3] = v[i][3] * g; }
;     asm volatile("s_waitcnt lgkmcnt(0)" ::: "memory");
;     const int c = lane & 7;
;     const int rbase = (mapmode == 0) ? n0 : (256 * (n0 >> 7) + (n0 & 127) + (mapmode == 2 ? 128 : 0));
; #pragma unroll
;     for (int j = 0; j < 8; ++j) { const int n = (lane >> 3) + 8 * j; const LAS float* sp = scr + (8 * c) * 65 + n;
;         u32x4 o; o.x = pg8::cvt_pk_bf16(sp[0 * 65], sp[1 * 65]); o.y = pg8::cvt_pk_bf16(sp[2 * 65], sp[3 * 65]); o.z = pg8::cvt_pk_bf16(sp[4 * 65], sp[5 * 65]); o.w = pg8::cvt_pk_bf16(sp[6 * 65], sp[7 * 65]);
;         *(u32x4*)(WT + (size_t)(rbase + n) * K + k0 + 8 * c) = o; }
;     asm volatile("s_waitcnt lgkmcnt(0)" ::: "memory");
	ds_write2_b32 v2, v54, v55 offset1:1
	v_add_u32_e32 v2, 0x34d8, v69
	ds_write2_b32 v2, v56, v57 offset1:1
	v_add_u32_e32 v2, 0x38e0, v69
	s_waitcnt vmcnt(1)
	ds_write2_b32 v2, v58, v59 offset1:1
	v_add_u32_e32 v2, 0x38e8, v69
	ds_write2_b32 v2, v60, v61 offset1:1
	v_add_u32_e32 v2, 0x3cf0, v69
	s_waitcnt vmcnt(0)
	ds_write2_b32 v2, v62, v63 offset1:1
	v_add_u32_e32 v2, 0x3cf8, v69
	ds_write2_b32 v2, v64, v65 offset1:1
	s_waitcnt lgkmcnt(0)
	ds_read2_b32 v[2:3], v131 offset1:65
	s_waitcnt lgkmcnt(0)
	v_cvt_pk_bf16_f32 v2, v2, v3
	ds_read2_b32 v[4:5], v131 offset0:130 offset1:195
	s_waitcnt lgkmcnt(0)
	v_cvt_pk_bf16_f32 v3, v4, v5
	ds_read2_b32 v[4:5], v12 offset0:4 offset1:69
	s_waitcnt lgkmcnt(0)
	v_cvt_pk_bf16_f32 v4, v4, v5
	ds_read2_b32 v[6:7], v12 offset0:134 offset1:199
	s_waitcnt lgkmcnt(0)
	v_cvt_pk_bf16_f32 v5, v6, v7
	global_store_dwordx4 v[10:11], v[2:5], off
	v_or_b32_e32 v10, v87, v73
	v_mul_u32_u24_e32 v10, 0xb00, v10
	ds_read2_b32 v[6:7], v131 offset0:8 offset1:73
	s_waitcnt lgkmcnt(0)
	v_cvt_pk_bf16_f32 v2, v6, v7
	ds_read2_b32 v[4:5], v131 offset0:138 offset1:203
	v_lshlrev_b32_e32 v78, 1, v10
	s_waitcnt lgkmcnt(0)
	v_cvt_pk_bf16_f32 v3, v4, v5
	ds_read2_b32 v[4:5], v12 offset0:12 offset1:77
	v_lshl_add_u64 v[10:11], v[8:9], 0, v[78:79]
	s_waitcnt lgkmcnt(0)
	v_cvt_pk_bf16_f32 v4, v4, v5
	ds_read2_b32 v[6:7], v12 offset0:142 offset1:207
	s_waitcnt lgkmcnt(0)
	v_cvt_pk_bf16_f32 v5, v6, v7
	global_store_dwordx4 v[10:11], v[2:5], off
	v_or_b32_e32 v10, v87, v77
	v_mul_u32_u24_e32 v10, 0xb00, v10
	ds_read2_b32 v[6:7], v131 offset0:16 offset1:81
	s_waitcnt lgkmcnt(0)
	v_cvt_pk_bf16_f32 v2, v6, v7
	ds_read2_b32 v[4:5], v131 offset0:146 offset1:211
	v_lshlrev_b32_e32 v78, 1, v10
	s_waitcnt lgkmcnt(0)
	v_cvt_pk_bf16_f32 v3, v4, v5
	ds_read2_b32 v[4:5], v12 offset0:20 offset1:85
	v_lshl_add_u64 v[10:11], v[8:9], 0, v[78:79]
	s_waitcnt lgkmcnt(0)
	v_cvt_pk_bf16_f32 v4, v4, v5
	ds_read2_b32 v[6:7], v12 offset0:150 offset1:215
	s_waitcnt lgkmcnt(0)
	v_cvt_pk_bf16_f32 v5, v6, v7
	global_store_dwordx4 v[10:11], v[2:5], off
	v_or_b32_e32 v10, v87, v81
	v_mul_u32_u24_e32 v10, 0xb00, v10
	ds_read2_b32 v[6:7], v131 offset0:24 offset1:89
	s_waitcnt lgkmcnt(0)
	v_cvt_pk_bf16_f32 v2, v6, v7
	ds_read2_b32 v[4:5], v131 offset0:154 offset1:219
	v_lshlrev_b32_e32 v78, 1, v10
	s_waitcnt lgkmcnt(0)
	v_cvt_pk_bf16_f32 v3, v4, v5
	ds_read2_b32 v[4:5], v12 offset0:28 offset1:93
	v_lshl_add_u64 v[10:11], v[8:9], 0, v[78:79]
	s_waitcnt lgkmcnt(0)
	v_cvt_pk_bf16_f32 v4, v4, v5
	ds_read2_b32 v[6:7], v12 offset0:158 offset1:223
	s_waitcnt lgkmcnt(0)
	v_cvt_pk_bf16_f32 v5, v6, v7
	global_store_dwordx4 v[10:11], v[2:5], off
	v_or_b32_e32 v10, v87, v95
	v_mul_u32_u24_e32 v10, 0xb00, v10
	ds_read2_b32 v[6:7], v131 offset0:32 offset1:97
	s_waitcnt lgkmcnt(0)
	v_cvt_pk_bf16_f32 v2, v6, v7
	ds_read2_b32 v[4:5], v131 offset0:162 offset1:227
	v_lshlrev_b32_e32 v78, 1, v10
	s_waitcnt lgkmcnt(0)
	v_cvt_pk_bf16_f32 v3, v4, v5
	ds_read2_b32 v[4:5], v12 offset0:36 offset1:101
	v_lshl_add_u64 v[10:11], v[8:9], 0, v[78:79]
	s_waitcnt lgkmcnt(0)
	v_cvt_pk_bf16_f32 v4, v4, v5
	ds_read2_b32 v[6:7], v12 offset0:166 offset1:231
	s_waitcnt lgkmcnt(0)
	v_cvt_pk_bf16_f32 v5, v6, v7
	global_store_dwordx4 v[10:11], v[2:5], off
	v_or_b32_e32 v10, v87, v96
	v_mul_u32_u24_e32 v10, 0xb00, v10
	ds_read2_b32 v[6:7], v131 offset0:40 offset1:105
	s_waitcnt lgkmcnt(0)
	v_cvt_pk_bf16_f32 v2, v6, v7
	ds_read2_b32 v[4:5], v131 offset0:170 offset1:235
	v_lshlrev_b32_e32 v78, 1, v10
	s_waitcnt lgkmcnt(0)
	v_cvt_pk_bf16_f32 v3, v4, v5
	ds_read2_b32 v[4:5], v12 offset0:44 offset1:109
	v_lshl_add_u64 v[10:11], v[8:9], 0, v[78:79]
	s_waitcnt lgkmcnt(0)
	v_cvt_pk_bf16_f32 v4, v4, v5
	ds_read2_b32 v[6:7], v12 offset0:174 offset1:239
	s_waitcnt lgkmcnt(0)
	v_cvt_pk_bf16_f32 v5, v6, v7
	global_store_dwordx4 v[10:11], v[2:5], off
	v_or_b32_e32 v10, v87, v97
	ds_read2_b32 v[6:7], v131 offset0:48 offset1:113
	s_waitcnt lgkmcnt(0)
	v_cvt_pk_bf16_f32 v2, v6, v7
	ds_read2_b32 v[4:5], v131 offset0:178 offset1:243
	v_mul_u32_u24_e32 v10, 0xb00, v10
	s_waitcnt lgkmcnt(0)
	v_cvt_pk_bf16_f32 v3, v4, v5
	ds_read2_b32 v[4:5], v12 offset0:52 offset1:117
	v_lshlrev_b32_e32 v78, 1, v10
	s_waitcnt lgkmcnt(0)
	v_cvt_pk_bf16_f32 v4, v4, v5
	ds_read2_b32 v[6:7], v12 offset0:182 offset1:247
	s_waitcnt lgkmcnt(0)
	v_cvt_pk_bf16_f32 v5, v6, v7
	v_lshl_add_u64 v[10:11], v[8:9], 0, v[78:79]
	ds_read2_b32 v[6:7], v131 offset0:56 offset1:121
	global_store_dwordx4 v[10:11], v[2:5], off
	s_waitcnt lgkmcnt(0)
	s_nop 0
	v_cvt_pk_bf16_f32 v2, v6, v7
	ds_read2_b32 v[4:5], v131 offset0:186 offset1:251
	s_waitcnt lgkmcnt(0)
	v_cvt_pk_bf16_f32 v3, v4, v5
	ds_read2_b32 v[4:5], v12 offset0:60 offset1:125
	s_waitcnt lgkmcnt(0)
	v_cvt_pk_bf16_f32 v4, v4, v5
	ds_read2_b32 v[6:7], v12 offset0:190 offset1:255
	s_waitcnt lgkmcnt(0)
	v_cvt_pk_bf16_f32 v5, v6, v7
	v_or_b32_e32 v6, v87, v98
	v_mul_u32_u24_e32 v6, 0xb00, v6
	v_lshlrev_b32_e32 v78, 1, v6
	v_lshl_add_u64 v[6:7], v[8:9], 0, v[78:79]
	global_store_dwordx4 v[6:7], v[2:5], off
	s_waitcnt lgkmcnt(0)

; #define LAS __attribute__((address_space(3)))
; __device__ __forceinline__ void transpose_item(const float* W, int K, int N, bf16_t* WT, int mapmode, const float* ga, const float* gb, int ksplit, int qcols, LAS float* scr, int item, int lane) {
;     const int nblk = N / 64, kb = item / nblk, nb = item % nblk, k0 = 64 * kb, n0 = 64 * nb;
;     const float cs = (n0 < qcols) ? 0.125f * 1.44269504088896f : 1.0f;
;     const int kl = lane >> 4, n4 = (lane & 15) * 4;
;     f32x4 v[16];
; #pragma unroll
;     for (int i = 0; i < 16; ++i) v[i] = *(const f32x4*)(W + (size_t)(k0 + 4 * i + kl) * N + n0 + n4);
; #pragma unroll
;     for (int i = 0; i < 16; ++i) { const int kk = 4 * i + kl, k = k0 + kk;
;         float g = cs; if (ga) g *= (k < ksplit) ? ga[k] : gb[k - ksplit];
;         LAS float* d = scr + kk * 65 + n4; d[0] = v[i][0] * g; d[1] = v[i][1] * g; d[2] = v[i][2] * g; d[3] = v[i][3] * g; }
; __device__ __forceinline__ void prologue(const Args& A, LAS unsigned char* lds) {
;     ...
;         if (r < I_G) { transpose_item(A.in[I_WUP] + (size_t)L * DM * DFF, DM, DFF, (bf16_t*)(wl + WO_GU), 2, A.in[I_GFFN] + L * DM, A.in[I_GFFN] + L * DM, DM, 0, scr, r, lane); continue; } r -= I_G;
.LBB0_45:
	s_andn2_saveexec_b64 s[42:43], s[42:43]
	s_cbranch_execz .LBB0_71
	v_add_u16_e32 v2, 0xf940, v3
	v_mul_u32_u24_e32 v3, 0xba2f, v2
	v_lshrrev_b32_e32 v3, 21, v3
	v_mul_lo_u16_e32 v6, 44, v3
	v_mov_b64_e32 v[4:5], s[14:15]
	v_sub_u16_e32 v87, v2, v6
	v_lshlrev_b32_e32 v86, 6, v3
	v_mad_i64_i32 v[4:5], s[0:1], v90, s65, v[4:5]
	v_or_b32_e32 v91, v86, v74
	v_lshlrev_b32_e32 v78, 8, v87
	v_lshl_add_u64 v[2:3], v[4:5], 0, v[78:79]
	v_lshlrev_b32_e32 v78, 2, v76
	v_mul_u32_u24_e32 v6, 0xb00, v91
	v_lshl_add_u64 v[2:3], v[2:3], 0, v[78:79]
	v_lshlrev_b32_e32 v78, 2, v6
	v_mad_u64_u32 v[4:5], s[0:1], v91, s66, v[2:3]
	v_lshl_add_u64 v[2:3], v[2:3], 0, v[78:79]
	v_add_co_u32_e32 v6, vcc, s67, v2
	v_lshlrev_b32_e32 v88, 10, v90
	s_nop 0
	v_addc_co_u32_e32 v7, vcc, 0, v3, vcc
	global_load_dwordx4 v[62:65], v[4:5], off nt
	global_load_dwordx4 v[58:61], v[6:7], off nt
	v_add_co_u32_e32 v4, vcc, s68, v2
	v_ashrrev_i32_e32 v89, 31, v88
	s_nop 0
	v_addc_co_u32_e32 v5, vcc, 0, v3, vcc
	v_add_co_u32_e32 v6, vcc, s69, v2
	v_cndmask_b32_e64 v78, 0, 1, s[26:27]
	s_nop 0
	v_addc_co_u32_e32 v7, vcc, 0, v3, vcc
	global_load_dwordx4 v[54:57], v[4:5], off nt
	global_load_dwordx4 v[50:53], v[6:7], off nt
	v_add_co_u32_e32 v4, vcc, s60, v2
	v_lshl_add_u64 v[88:89], v[88:89], 2, s[10:11]
	s_nop 0
	v_addc_co_u32_e32 v5, vcc, 0, v3, vcc
	v_add_co_u32_e32 v6, vcc, s70, v2
	v_cmp_ne_u32_e64 s[0:1], 1, v78
	s_nop 0
	v_addc_co_u32_e32 v7, vcc, 0, v3, vcc
	global_load_dwordx4 v[46:49], v[4:5], off nt
	global_load_dwordx4 v[42:45], v[6:7], off nt
	v_add_co_u32_e32 v4, vcc, s71, v2
	v_add_lshl_u32 v90, v86, v74, 2
	s_nop 0
	v_addc_co_u32_e32 v5, vcc, 0, v3, vcc
	v_add_co_u32_e32 v6, vcc, s72, v2
	s_nop 1
	v_addc_co_u32_e32 v7, vcc, 0, v3, vcc
	global_load_dwordx4 v[38:41], v[4:5], off nt
	global_load_dwordx4 v[34:37], v[6:7], off nt
	v_add_co_u32_e32 v4, vcc, s73, v2
	s_nop 1
	v_addc_co_u32_e32 v5, vcc, 0, v3, vcc
	v_add_co_u32_e32 v6, vcc, s74, v2
	s_nop 1
	v_addc_co_u32_e32 v7, vcc, 0, v3, vcc
	global_load_dwordx4 v[30:33], v[4:5], off nt
	global_load_dwordx4 v[26:29], v[6:7], off nt
	v_add_co_u32_e32 v4, vcc, s75, v2
	s_nop 1
	v_addc_co_u32_e32 v5, vcc, 0, v3, vcc
	v_add_co_u32_e32 v6, vcc, s76, v2
	s_nop 1
	v_addc_co_u32_e32 v7, vcc, 0, v3, vcc
	global_load_dwordx4 v[22:25], v[4:5], off nt
	global_load_dwordx4 v[18:21], v[6:7], off nt
	v_add_co_u32_e32 v4, vcc, s77, v2
	s_nop 1
	v_addc_co_u32_e32 v5, vcc, 0, v3, vcc
	v_add_co_u32_e32 v6, vcc, 0x8f000, v2
	s_nop 1
	v_addc_co_u32_e32 v7, vcc, 0, v3, vcc
	global_load_dwordx4 v[14:17], v[4:5], off nt
	global_load_dwordx4 v[10:13], v[6:7], off nt
	v_add_co_u32_e32 v4, vcc, 0x9a000, v2
	s_nop 1
	v_addc_co_u32_e32 v5, vcc, 0, v3, vcc
	v_add_co_u32_e32 v2, vcc, 0xa5000, v2
	s_nop 1
	v_addc_co_u32_e32 v3, vcc, 0, v3, vcc
	global_load_dwordx4 v[6:9], v[4:5], off nt
	s_nop 0
	global_load_dwordx4 v[2:5], v[2:3], off nt
	s_andn2_b64 vcc, exec, s[26:27]
	s_cbranch_vccnz .LBB0_175
	v_lshlrev_b32_e32 v78, 2, v91
	v_lshl_add_u64 v[92:93], v[88:89], 0, v[78:79]
	v_mov_b32_e32 v91, v79
	global_load_dword v92, v[92:93], off
	v_lshl_add_u64 v[132:133], v[88:89], 0, v[90:91]
	global_load_dword v78, v[132:133], off offset:16
	s_waitcnt vmcnt(1)
	v_pk_mul_f32 v[132:133], v[62:63], v[92:93] op_sel_hi:[1,0]
	v_pk_mul_f32 v[92:93], v[64:65], v[92:93] op_sel_hi:[1,0]
	ds_write2_b32 v69, v132, v133 offset1:1
	ds_write2_b32 v69, v92, v93 offset0:2 offset1:3
	s_cbranch_execnz .LBB0_49

; #define LAS __attribute__((address_space(3)))
; __device__ __forceinline__ void transpose_item(const float* W, int K, int N, bf16_t* WT, int mapmode, const float* ga, const float* gb, int ksplit, int qcols, LAS float* scr, int item, int lane) {
;     const int nblk = N / 64, kb = item / nblk, nb = item % nblk, k0 = 64 * kb, n0 = 64 * nb;
;     const float cs = (n0 < qcols) ? 0.125f * 1.44269504088896f : 1.0f;
;     const int kl = lane >> 4, n4 = (lane & 15) * 4;
;     f32x4 v[16];
; #pragma unroll
;     for (int i = 0; i < 16; ++i) v[i] = *(const f32x4*)(W + (size_t)(k0 + 4 * i + kl) * N + n0 + n4);
; #pragma unroll
;     for (int i = 0; i < 16; ++i) { const int kk = 4 * i + kl, k = k0 + kk;
;         float g = cs; if (ga) g *= (k < ksplit) ? ga[k] : gb[k - ksplit];
;         LAS float* d = scr + kk * 65 + n4; d[0] = v[i][0] * g; d[1] = v[i][1] * g; d[2] = v[i][2] * g; d[3] = v[i][3] * g; }
; __device__ __forceinline__ void prologue(const Args& A, LAS unsigned char* lds) {
;     ...
;         if (r < I_G) { transpose_item(A.in[I_WGATE] + (size_t)L * DM * DFF, DM, DFF, (bf16_t*)(wl + WO_GU), 1, A.in[I_GFFN] + L * DM, A.in[I_GFFN] + L * DM, DM, 0, scr, r, lane); continue; } r -= I_G;
.LBB0_72:
	s_andn2_saveexec_b64 s[40:41], s[40:41]
	s_cbranch_execz .LBB0_98
	v_add_u16_e32 v2, 0xfc00, v3
	v_mul_u32_u24_e32 v3, 0xba2f, v2
	v_lshrrev_b32_e32 v3, 21, v3
	v_mul_lo_u16_e32 v6, 44, v3
	v_mov_b64_e32 v[4:5], s[12:13]
	v_sub_u16_e32 v87, v2, v6
	v_lshlrev_b32_e32 v86, 6, v3
	v_mad_i64_i32 v[4:5], s[0:1], v90, s65, v[4:5]
	v_or_b32_e32 v91, v86, v74
	v_lshlrev_b32_e32 v78, 8, v87
	v_lshl_add_u64 v[2:3], v[4:5], 0, v[78:79]
	v_lshlrev_b32_e32 v78, 2, v76
	v_mul_u32_u24_e32 v6, 0xb00, v91
	v_lshl_add_u64 v[2:3], v[2:3], 0, v[78:79]
	v_lshlrev_b32_e32 v78, 2, v6
	v_mad_u64_u32 v[4:5], s[0:1], v91, s66, v[2:3]
	v_lshl_add_u64 v[2:3], v[2:3], 0, v[78:79]
	v_add_co_u32_e32 v6, vcc, s67, v2
	v_lshlrev_b32_e32 v88, 10, v90
	s_nop 0
	v_addc_co_u32_e32 v7, vcc, 0, v3, vcc
	global_load_dwordx4 v[62:65], v[4:5], off nt
	global_load_dwordx4 v[58:61], v[6:7], off nt
	v_add_co_u32_e32 v4, vcc, s68, v2
	v_ashrrev_i32_e32 v89, 31, v88
	s_nop 0
	v_addc_co_u32_e32 v5, vcc, 0, v3, vcc
	v_add_co_u32_e32 v6, vcc, s69, v2
	v_cndmask_b32_e64 v78, 0, 1, s[26:27]
	s_nop 0
	v_addc_co_u32_e32 v7, vcc, 0, v3, vcc
	global_load_dwordx4 v[54:57], v[4:5], off nt
	global_load_dwordx4 v[50:53], v[6:7], off nt
	v_add_co_u32_e32 v4, vcc, s60, v2
	v_lshl_add_u64 v[88:89], v[88:89], 2, s[10:11]
	s_nop 0
	v_addc_co_u32_e32 v5, vcc, 0, v3, vcc
	v_add_co_u32_e32 v6, vcc, s70, v2
	v_cmp_ne_u32_e64 s[0:1], 1, v78
	s_nop 0
	v_addc_co_u32_e32 v7, vcc, 0, v3, vcc
	global_load_dwordx4 v[46:49], v[4:5], off nt
	global_load_dwordx4 v[42:45], v[6:7], off nt
	v_add_co_u32_e32 v4, vcc, s71, v2
	v_add_lshl_u32 v90, v86, v74, 2
	s_nop 0
	v_addc_co_u32_e32 v5, vcc, 0, v3, vcc
	v_add_co_u32_e32 v6, vcc, s72, v2
	s_nop 1
	v_addc_co_u32_e32 v7, vcc, 0, v3, vcc
	global_load_dwordx4 v[38:41], v[4:5], off nt
	global_load_dwordx4 v[34:37], v[6:7], off nt
	v_add_co_u32_e32 v4, vcc, s73, v2
	s_nop 1
	v_addc_co_u32_e32 v5, vcc, 0, v3, vcc
	v_add_co_u32_e32 v6, vcc, s74, v2
	s_nop 1
	v_addc_co_u32_e32 v7, vcc, 0, v3, vcc
	global_load_dwordx4 v[30:33], v[4:5], off nt
	global_load_dwordx4 v[26:29], v[6:7], off nt
	v_add_co_u32_e32 v4, vcc, s75, v2
	s_nop 1
	v_addc_co_u32_e32 v5, vcc, 0, v3, vcc
	v_add_co_u32_e32 v6, vcc, s76, v2
	s_nop 1
	v_addc_co_u32_e32 v7, vcc, 0, v3, vcc
	global_load_dwordx4 v[22:25], v[4:5], off nt
	global_load_dwordx4 v[18:21], v[6:7], off nt
	v_add_co_u32_e32 v4, vcc, s77, v2
	s_nop 1
	v_addc_co_u32_e32 v5, vcc, 0, v3, vcc
	v_add_co_u32_e32 v6, vcc, 0x8f000, v2
	s_nop 1
	v_addc_co_u32_e32 v7, vcc, 0, v3, vcc
	global_load_dwordx4 v[14:17], v[4:5], off nt
	global_load_dwordx4 v[10:13], v[6:7], off nt
	v_add_co_u32_e32 v4, vcc, 0x9a000, v2
	s_nop 1
	v_addc_co_u32_e32 v5, vcc, 0, v3, vcc
	v_add_co_u32_e32 v2, vcc, 0xa5000, v2
	s_nop 1
	v_addc_co_u32_e32 v3, vcc, 0, v3, vcc
	global_load_dwordx4 v[6:9], v[4:5], off nt
	s_nop 0
	global_load_dwordx4 v[2:5], v[2:3], off nt
	s_andn2_b64 vcc, exec, s[26:27]
	s_cbranch_vccnz .LBB0_167
	v_lshlrev_b32_e32 v78, 2, v91
	v_lshl_add_u64 v[92:93], v[88:89], 0, v[78:79]
	v_mov_b32_e32 v91, v79
	global_load_dword v92, v[92:93], off
	v_lshl_add_u64 v[132:133], v[88:89], 0, v[90:91]
	global_load_dword v78, v[132:133], off offset:16
	s_waitcnt vmcnt(1)
	v_pk_mul_f32 v[132:133], v[62:63], v[92:93] op_sel_hi:[1,0]
	v_pk_mul_f32 v[92:93], v[64:65], v[92:93] op_sel_hi:[1,0]
	ds_write2_b32 v69, v132, v133 offset1:1
	ds_write2_b32 v69, v92, v93 offset0:2 offset1:3
	s_cbranch_execnz .LBB0_76

; #define LAS __attribute__((address_space(3)))
; __device__ __forceinline__ void transpose_item(const float* W, int K, int N, bf16_t* WT, int mapmode, const float* ga, const float* gb, int ksplit, int qcols, LAS float* scr, int item, int lane) {
;     const int nblk = N / 64, kb = item / nblk, nb = item % nblk, k0 = 64 * kb, n0 = 64 * nb;
;     const float cs = (n0 < qcols) ? 0.125f * 1.44269504088896f : 1.0f;
;     const int kl = lane >> 4, n4 = (lane & 15) * 4;
;     f32x4 v[16];
; #pragma unroll
;     for (int i = 0; i < 16; ++i) v[i] = *(const f32x4*)(W + (size_t)(k0 + 4 * i + kl) * N + n0 + n4);
; #pragma unroll
;     for (int i = 0; i < 16; ++i) { const int kk = 4 * i + kl, k = k0 + kk;
;         float g = cs; if (ga) g *= (k < ksplit) ? ga[k] : gb[k - ksplit];
;         LAS float* d = scr + kk * 65 + n4; d[0] = v[i][0] * g; d[1] = v[i][1] * g; d[2] = v[i][2] * g; d[3] = v[i][3] * g; }
; __device__ __forceinline__ void prologue(const Args& A, LAS unsigned char* lds) {
;     ...
;         if (r < I_OUT) { transpose_item(A.in[I_WOUT] + (size_t)L * DM * DM, DM, DM, (bf16_t*)(wl + WO_OUT), 0, A.in[I_GATT] + L * 512, A.in[I_GCONV] + L * 512, 512, 0, scr, r, lane); continue; } r -= I_OUT;
.LBB0_99:
	s_andn2_saveexec_b64 s[40:41], s[4:5]
	s_cbranch_execz .LBB0_125
	v_lshlrev_b32_e32 v3, 2, v2
	v_lshlrev_b32_e32 v2, 6, v2
	v_sub_u32_e32 v2, v125, v2
	v_lshlrev_b64 v[4:5], 22, v[90:91]
	v_sub_u32_e32 v3, v126, v3
	v_and_b32_e32 v93, 0x3c0, v2
	v_lshl_add_u64 v[4:5], s[8:9], 0, v[4:5]
	v_and_b32_e32 v78, 0x3c0, v3
	v_lshlrev_b32_e32 v2, 2, v93
	v_mov_b32_e32 v3, v79
	v_or_b32_e32 v91, v78, v74
	v_lshl_add_u64 v[2:3], v[4:5], 0, v[2:3]
	v_lshlrev_b32_e32 v4, 2, v76
	v_mov_b32_e32 v5, v79
	v_lshl_add_u64 v[2:3], v[2:3], 0, v[4:5]
	v_lshlrev_b32_e32 v4, 12, v91
	v_lshl_add_u64 v[2:3], v[2:3], 0, v[4:5]
	v_add_co_u32_e32 v4, vcc, s86, v2
	v_lshlrev_b32_e32 v86, 9, v90
	s_nop 0
	v_addc_co_u32_e32 v5, vcc, 0, v3, vcc
	global_load_dwordx4 v[62:65], v[2:3], off nt
	global_load_dwordx4 v[58:61], v[4:5], off nt
	v_add_co_u32_e32 v4, vcc, s87, v2
	v_ashrrev_i32_e32 v87, 31, v86
	s_nop 0
	v_addc_co_u32_e32 v5, vcc, 0, v3, vcc
	v_add_co_u32_e32 v6, vcc, s89, v2
	v_readlane_b32 s44, v254, 4
	s_nop 0
	v_addc_co_u32_e32 v7, vcc, 0, v3, vcc
	global_load_dwordx4 v[54:57], v[4:5], off nt
	global_load_dwordx4 v[50:53], v[6:7], off nt
	v_add_co_u32_e32 v4, vcc, s90, v2
	v_lshlrev_b64 v[86:87], 2, v[86:87]
	s_nop 0
	v_addc_co_u32_e32 v5, vcc, 0, v3, vcc
	v_add_co_u32_e32 v6, vcc, s91, v2
	v_readlane_b32 s56, v254, 16
	s_nop 0
	v_addc_co_u32_e32 v7, vcc, 0, v3, vcc
	global_load_dwordx4 v[46:49], v[4:5], off nt
	global_load_dwordx4 v[42:45], v[6:7], off nt
	v_add_co_u32_e32 v4, vcc, s92, v2
	v_readlane_b32 s57, v254, 17
	s_nop 0
	v_addc_co_u32_e32 v5, vcc, 0, v3, vcc
	v_add_co_u32_e32 v6, vcc, s93, v2
	v_readlane_b32 s58, v254, 18
	s_nop 0
	v_addc_co_u32_e32 v7, vcc, 0, v3, vcc
	global_load_dwordx4 v[38:41], v[4:5], off nt
	global_load_dwordx4 v[34:37], v[6:7], off nt
	v_add_co_u32_e32 v4, vcc, s94, v2
	v_readlane_b32 s59, v254, 19
	s_nop 0
	v_addc_co_u32_e32 v5, vcc, 0, v3, vcc
	v_add_co_u32_e32 v6, vcc, s95, v2
	v_cndmask_b32_e64 v90, 0, 1, s[28:29]
	s_nop 0
	v_addc_co_u32_e32 v7, vcc, 0, v3, vcc
	global_load_dwordx4 v[30:33], v[4:5], off nt
	global_load_dwordx4 v[26:29], v[6:7], off nt
	v_add_co_u32_e32 v4, vcc, s96, v2
	v_lshl_add_u64 v[88:89], s[56:57], 0, v[86:87]
	s_nop 0
	v_addc_co_u32_e32 v5, vcc, 0, v3, vcc
	v_add_co_u32_e32 v6, vcc, s60, v2
	v_lshl_add_u64 v[86:87], s[58:59], 0, v[86:87]
	s_nop 0
	v_addc_co_u32_e32 v7, vcc, 0, v3, vcc
	global_load_dwordx4 v[22:25], v[4:5], off nt
	global_load_dwordx4 v[18:21], v[6:7], off nt
	v_add_co_u32_e32 v4, vcc, s61, v2
	v_cmp_ne_u32_e64 s[0:1], 1, v90
	s_nop 0
	v_addc_co_u32_e32 v5, vcc, 0, v3, vcc
	v_add_co_u32_e32 v6, vcc, 0x34000, v2
	v_cmp_gt_u32_e64 s[4:5], s78, v78
	s_nop 0
	v_addc_co_u32_e32 v7, vcc, 0, v3, vcc
	global_load_dwordx4 v[14:17], v[4:5], off nt
	global_load_dwordx4 v[10:13], v[6:7], off nt
	v_add_co_u32_e32 v4, vcc, 0x38000, v2
	v_add_lshl_u32 v90, v78, v74, 2
	s_nop 0
	v_addc_co_u32_e32 v5, vcc, 0, v3, vcc
	v_add_co_u32_e32 v2, vcc, 0x3c000, v2
	v_readlane_b32 s45, v254, 5
	s_nop 0
	v_addc_co_u32_e32 v3, vcc, 0, v3, vcc
	global_load_dwordx4 v[6:9], v[4:5], off nt
	s_nop 0
	global_load_dwordx4 v[2:5], v[2:3], off nt
	s_andn2_b64 vcc, exec, s[28:29]
	v_readlane_b32 s46, v254, 6
	v_readlane_b32 s47, v254, 7
	v_readlane_b32 s48, v254, 8
	v_readlane_b32 s49, v254, 9
	v_readlane_b32 s50, v254, 10
	v_readlane_b32 s51, v254, 11
	v_readlane_b32 s52, v254, 12
	v_readlane_b32 s53, v254, 13
	v_readlane_b32 s54, v254, 14
	v_readlane_b32 s55, v254, 15
	s_cbranch_vccnz .LBB0_159
	v_lshlrev_b32_e32 v132, 2, v91
	v_mov_b32_e32 v133, v79
	s_movk_i32 s42, 0xf800
	v_lshl_add_u64 v[134:135], v[88:89], 0, v[132:133]
	v_lshl_add_u64 v[132:133], v[86:87], 0, v[132:133]
	s_mov_b32 s43, -1
	v_lshl_add_u64 v[132:133], v[132:133], 0, s[42:43]
	v_cndmask_b32_e64 v133, v133, v135, s[4:5]
	v_cndmask_b32_e64 v132, v132, v134, s[4:5]
	v_mov_b32_e32 v91, v79
	s_movk_i32 s42, 0xf810
	global_load_dword v94, v[132:133], off
	v_lshl_add_u64 v[132:133], v[88:89], 0, v[90:91]
	v_lshl_add_u64 v[134:135], v[86:87], 0, v[90:91]
	s_mov_b32 s43, -1
	v_lshl_add_u64 v[132:133], v[132:133], 0, 16
	v_lshl_add_u64 v[134:135], v[134:135], 0, s[42:43]
	v_cndmask_b32_e64 v133, v135, v133, s[4:5]
	v_cndmask_b32_e64 v132, v134, v132, s[4:5]
	global_load_dword v92, v[132:133], off
	s_waitcnt vmcnt(1)
	v_pk_mul_f32 v[132:133], v[62:63], v[94:95] op_sel_hi:[1,0]
	v_pk_mul_f32 v[134:135], v[64:65], v[94:95] op_sel_hi:[1,0]
	ds_write2_b32 v69, v132, v133 offset1:1
	ds_write2_b32 v69, v134, v135 offset0:2 offset1:3
	s_cbranch_execnz .LBB0_103

; #define LAS __attribute__((address_space(3)))
; __device__ __forceinline__ void transpose_item(const float* W, int K, int N, bf16_t* WT, int mapmode, const float* ga, const float* gb, int ksplit, int qcols, LAS float* scr, int item, int lane) {
;     const int nblk = N / 64, kb = item / nblk, nb = item % nblk, k0 = 64 * kb, n0 = 64 * nb;
;     const float cs = (n0 < qcols) ? 0.125f * 1.44269504088896f : 1.0f;
;     const int kl = lane >> 4, n4 = (lane & 15) * 4;
;     f32x4 v[16];
; #pragma unroll
;     for (int i = 0; i < 16; ++i) v[i] = *(const f32x4*)(W + (size_t)(k0 + 4 * i + kl) * N + n0 + n4);
; #pragma unroll
;     for (int i = 0; i < 16; ++i) { const int kk = 4 * i + kl, k = k0 + kk;
;         float g = cs; if (ga) g *= (k < ksplit) ? ga[k] : gb[k - ksplit];
;         LAS float* d = scr + kk * 65 + n4; d[0] = v[i][0] * g; d[1] = v[i][1] * g; d[2] = v[i][2] * g; d[3] = v[i][3] * g; }
; __device__ __forceinline__ void prologue(const Args& A, LAS unsigned char* lds) {
;     ...
;         if (r < I_IN) { transpose_item(A.in[I_WIN] + (size_t)L * DM * NIN, DM, NIN, (bf16_t*)(wl + WO_IN), 0, A.in[I_GMIX] + L * DM, A.in[I_GMIX] + L * DM, DM, 512, scr, r, lane); continue; } r -= I_IN;
.LBB0_126:
	s_andn2_saveexec_b64 s[38:39], s[38:39]
	s_cbranch_execz .LBB0_7
	v_mul_i32_i24_e32 v2, 0x2aab, v3
	v_lshrrev_b32_e32 v6, 31, v2
	v_ashrrev_i32_e32 v2, 19, v2
	v_add_u16_e32 v2, v2, v6
	v_readlane_b32 s40, v254, 4
	v_mul_lo_u16_e32 v6, 48, v2
	v_readlane_b32 s46, v254, 10
	v_readlane_b32 s47, v254, 11
	v_sub_u16_e32 v93, v3, v6
	s_mov_b32 s0, 0xc00000
	v_mov_b64_e32 v[4:5], s[46:47]
	v_lshlrev_b32_sdwa v88, v127, sext(v2) dst_sel:DWORD dst_unused:UNUSED_PAD src0_sel:DWORD src1_sel:WORD_0
	v_lshlrev_b32_sdwa v86, v127, sext(v93) dst_sel:DWORD dst_unused:UNUSED_PAD src0_sel:DWORD src1_sel:WORD_0
	v_mad_i64_i32 v[4:5], s[0:1], v90, s0, v[4:5]
	v_or_b32_e32 v92, v88, v74
	v_ashrrev_i32_e32 v87, 31, v86
	v_lshl_add_u64 v[2:3], v[86:87], 2, v[4:5]
	v_lshlrev_b32_e32 v78, 2, v76
	v_mul_i32_i24_e32 v6, 0xc00, v92
	v_lshl_add_u64 v[2:3], v[2:3], 0, v[78:79]
	v_mul_hi_i32_i24_e32 v5, 0x3000, v92
	v_mul_i32_i24_e32 v4, 0x3000, v92
	v_ashrrev_i32_e32 v7, 31, v6
	v_lshl_add_u64 v[4:5], v[2:3], 0, v[4:5]
	v_lshl_add_u64 v[2:3], v[6:7], 2, v[2:3]
	v_add_co_u32_e32 v6, vcc, s89, v2
	s_mov_b32 s0, 0x48000
	s_nop 0
	v_addc_co_u32_e32 v7, vcc, 0, v3, vcc
	global_load_dwordx4 v[62:65], v[4:5], off nt
	global_load_dwordx4 v[58:61], v[6:7], off nt
	v_add_co_u32_e32 v4, vcc, s92, v2
	v_lshlrev_b32_e32 v90, 10, v90
	s_nop 0
	v_addc_co_u32_e32 v5, vcc, 0, v3, vcc
	v_add_co_u32_e32 v6, vcc, s95, v2
	v_readlane_b32 s44, v254, 8
	s_nop 0
	v_addc_co_u32_e32 v7, vcc, 0, v3, vcc
	global_load_dwordx4 v[54:57], v[4:5], off nt
	global_load_dwordx4 v[50:53], v[6:7], off nt
	v_add_co_u32_e32 v4, vcc, s61, v2
	v_readlane_b32 s45, v254, 9
	s_nop 0
	v_addc_co_u32_e32 v5, vcc, 0, v3, vcc
	v_add_co_u32_e32 v6, vcc, s64, v2
	v_ashrrev_i32_e32 v91, 31, v90
	s_nop 0
	v_addc_co_u32_e32 v7, vcc, 0, v3, vcc
	global_load_dwordx4 v[46:49], v[4:5], off nt
	global_load_dwordx4 v[42:45], v[6:7], off nt
	v_add_co_u32_e32 v4, vcc, s0, v2
	s_mov_b32 s0, 0x54000
	s_nop 0
	v_addc_co_u32_e32 v5, vcc, 0, v3, vcc
	v_add_co_u32_e32 v6, vcc, s0, v2
	s_mov_b32 s0, 0x60000
	s_nop 0
	v_addc_co_u32_e32 v7, vcc, 0, v3, vcc
	global_load_dwordx4 v[38:41], v[4:5], off nt
	global_load_dwordx4 v[34:37], v[6:7], off nt
	v_add_co_u32_e32 v4, vcc, s0, v2
	s_mov_b32 s0, 0x6c000
	s_nop 0
	v_addc_co_u32_e32 v5, vcc, 0, v3, vcc
	v_add_co_u32_e32 v6, vcc, s0, v2
	s_mov_b32 s0, 0x78000
	s_nop 0
	v_addc_co_u32_e32 v7, vcc, 0, v3, vcc
	v_add_co_u32_e32 v8, vcc, s0, v2
	s_mov_b32 s0, 0x90000
	s_nop 0
	v_addc_co_u32_e32 v9, vcc, 0, v3, vcc
	v_add_co_u32_e32 v10, vcc, s77, v2
	v_cndmask_b32_e64 v78, 0, 1, s[30:31]
	s_nop 0
	v_addc_co_u32_e32 v11, vcc, 0, v3, vcc
	v_add_co_u32_e32 v12, vcc, s0, v2
	s_mov_b32 s0, 0x9c000
	s_nop 0
	v_addc_co_u32_e32 v13, vcc, 0, v3, vcc
	v_add_co_u32_e32 v132, vcc, s0, v2
	v_cmp_gt_i16_e64 s[4:5], 8, v93
	s_nop 0
	v_addc_co_u32_e32 v133, vcc, 0, v3, vcc
	v_add_co_u32_e32 v134, vcc, 0xa8000, v2
	v_lshl_add_u64 v[90:91], v[90:91], 2, s[44:45]
	s_nop 0
	v_addc_co_u32_e32 v135, vcc, 0, v3, vcc
	v_add_co_u32_e32 v2, vcc, 0xb4000, v2
	v_cmp_ne_u32_e64 s[0:1], 1, v78
	s_nop 0
	v_addc_co_u32_e32 v3, vcc, 0, v3, vcc
	global_load_dwordx4 v[30:33], v[4:5], off nt
	global_load_dwordx4 v[26:29], v[6:7], off nt
	global_load_dwordx4 v[22:25], v[8:9], off nt
	global_load_dwordx4 v[18:21], v[10:11], off nt
	global_load_dwordx4 v[14:17], v[12:13], off nt
	s_nop 0
	global_load_dwordx4 v[10:13], v[132:133], off nt
	global_load_dwordx4 v[6:9], v[134:135], off nt
	s_nop 0
	global_load_dwordx4 v[2:5], v[2:3], off nt
	s_andn2_b64 vcc, exec, s[30:31]
	v_ashrrev_i32_e32 v89, 31, v88
	v_cndmask_b32_e64 v78, 1.0, v128, s[4:5]
	v_readlane_b32 s41, v254, 5
	v_readlane_b32 s42, v254, 6
	v_readlane_b32 s43, v254, 7
	v_readlane_b32 s48, v254, 12
	v_readlane_b32 s49, v254, 13
	v_readlane_b32 s50, v254, 14
	v_readlane_b32 s51, v254, 15
	v_readlane_b32 s52, v254, 16
	v_readlane_b32 s53, v254, 17
	v_readlane_b32 s54, v254, 18
	v_readlane_b32 s55, v254, 19
	s_cbranch_vccnz .LBB0_150
	v_ashrrev_i32_e32 v93, 31, v92
	v_cmp_gt_i32_e32 vcc, s79, v92
	v_lshl_add_u64 v[132:133], v[92:93], 2, v[90:91]
	v_or_b32_e32 v94, v88, v99
	v_cndmask_b32_e64 v93, -1, 0, vcc
	v_cndmask_b32_e64 v92, v129, 0, vcc
	v_lshl_add_u64 v[92:93], v[132:133], 0, v[92:93]
	global_load_dword v87, v[92:93], off
	v_lshl_add_u64 v[92:93], v[88:89], 0, v[74:75]
	v_cmp_gt_i32_e32 vcc, s79, v94
	v_lshl_add_u64 v[92:93], v[92:93], 2, v[90:91]
	s_nop 0
	v_cndmask_b32_e64 v133, -1, 0, vcc
	v_cndmask_b32_e64 v132, v129, 0, vcc
	v_lshl_add_u64 v[92:93], v[92:93], 0, v[132:133]
	global_load_dword v94, v[92:93], off offset:16
	s_waitcnt vmcnt(1)
	v_mul_f32_e32 v92, v78, v87
	v_pk_mul_f32 v[132:133], v[62:63], v[92:93] op_sel_hi:[1,0]
	v_pk_mul_f32 v[92:93], v[64:65], v[92:93] op_sel_hi:[1,0]
	ds_write2_b32 v69, v132, v133 offset1:1
	ds_write2_b32 v69, v92, v93 offset0:2 offset1:3
	s_waitcnt vmcnt(0)
	v_mul_f32_e32 v94, v78, v94
	v_mov_b64_e32 v[92:93], v[94:95]
	s_cbranch_execnz .LBB0_130
